# logical workgroup id: slot bits 0 and 2 swapped (role bit = hardware slot bit 2; partial-round set unchanged)
# baseline (speedup 1.0000x reference)
; #define LAS __attribute__((address_space(3)))
; __global__ void __launch_bounds__(512, 2) fwd_megakernel(Args a) {
;     extern __shared__ __attribute__((aligned(16))) unsigned char lds_raw[];
;     LAS unsigned char* lds = (LAS unsigned char*)lds_raw;
;     cg::grid_group grid = cg::this_grid();
;     const int bid = blockIdx.x, G = gridDim.x;
;     if (threadIdx.x < 64) ((LAS unsigned*)(lds + 131072))[threadIdx.x] = 0u;
;     __syncthreads();
;     (void)xcd_barrier_post((unsigned*)(a.ws + WS_BAR), (volatile LAS unsigned*)(lds + 131072) + 8);
_Z14fwd_megakernel4Args:
	s_load_dwordx4 s[76:79], s[0:1], 0x80
	s_load_dwordx2 s[42:43], s[0:1], 0x90
	s_add_u32 s6, s0, 0x90
	v_and_b32_e32 v208, 0x3ff, v0
	s_mov_b32 s71, s2
	s_addc_u32 s7, s1, 0
	v_cmp_gt_u32_e32 vcc, 64, v208
	s_and_saveexec_b64 s[4:5], vcc
	v_lshl_add_u32 v1, v208, 2, 0
	v_add_u32_e32 v1, 0x20000, v1
	v_mov_b32_e32 v2, 0
	ds_write_b32 v1, v2
	s_or_b64 exec, exec, s[4:5]
	s_load_dword s2, s[0:1], 0x98
	s_waitcnt lgkmcnt(0)
	s_cmp_lg_u32 s42, 0x100
	s_cbranch_scc1 .Lperm_skip
	s_and_b32 s8, s71, 7
	s_lshr_b32 s9, s71, 3
	s_bfe_u32 s10, s9, 0x10002
	s_and_b32 s11, s9, 1
	s_xor_b32 s10, s10, s11
	s_lshl_b32 s11, s10, 2
	s_or_b32 s10, s10, s11
	s_xor_b32 s9, s9, s10
	s_lshl_b32 s9, s9, 3
	s_or_b32 s71, s9, s8
